# barrier release flags written with write-through stores (sc0 sc1) instead of 256 atomics
# speedup vs baseline: 1.0316x; 1.0009x over previous
.Ltail_end:
.LBB0_175:
	v_readlane_b32 s4, v254, 49
	s_add_i32 s14, s4, 2
	v_readlane_b32 s4, v252, 9
	v_readlane_b32 s5, v252, 10
	s_cmp_ge_i32 s14, s5
	s_waitcnt lgkmcnt(0)
	s_barrier
	s_cbranch_scc1 .LBB0_229
	s_waitcnt vmcnt(0)
	s_barrier
	s_mov_b64 s[4:5], exec
	v_readlane_b32 s6, v252, 31
	v_readlane_b32 s7, v252, 32
	s_mul_i32 s72, s62, 5
	s_add_i32 s72, s72, 2
	s_and_b64 s[6:7], s[4:5], s[6:7]
	s_mov_b64 exec, s[6:7]
	s_cbranch_execz .LBB0_228
	v_readlane_b32 s10, v253, 57
	v_readlane_b32 s11, v253, 58
	v_readlane_b32 s73, v254, 38
	v_mov_b32_e32 v2, 1
	s_nop 4
	global_atomic_add v3, v1, v2, s[10:11] sc0
	v_mov_b32_e32 v0, s73
	v_readlane_b32 s73, v254, 39
	ds_read_b32 v4, v0
	s_nop 1
	v_mov_b32_e32 v0, s73
	ds_read_b32 v5, v0
	s_waitcnt lgkmcnt(0)
	v_mul_lo_u32 v4, v4, s72
	v_mul_lo_u32 v5, v5, s72
	s_waitcnt vmcnt(0)
	v_add_u32_e32 v3, 1, v3
	v_cmp_eq_u32_e32 vcc, v3, v4
	s_cbranch_vccz .Lxb1_poll
	buffer_wbl2 sc1
	v_readlane_b32 s10, v253, 61
	v_readlane_b32 s11, v253, 62
	s_waitcnt vmcnt(0)
	s_nop 4
	global_atomic_add v3, v1, v2, s[10:11] sc0
	s_waitcnt vmcnt(0)
	v_add_u32_e32 v3, 1, v3
	v_cmp_eq_u32_e32 vcc, v3, v5
	s_cbranch_vccz .Lxb1_poll
	s_add_u32 s10, s30, 0x8400
	s_addc_u32 s11, s31, 0
	s_mov_b64 exec, -1
	v_mbcnt_lo_u32_b32 v3, -1, 0
	v_mbcnt_hi_u32_b32 v3, -1, v3
	s_sub_u32 s73, s72, 1
	v_mov_b32_e32 v2, s73
	v_lshlrev_b32_e32 v3, 5, v3
	s_nop 1
	global_store_dword v3, v2, s[10:11] sc0 sc1
	global_store_dword v3, v2, s[10:11] offset:2048 sc0 sc1
	s_add_u32 s10, s10, 0x1000
	s_addc_u32 s11, s11, 0
	global_store_dword v3, v2, s[10:11] sc0 sc1
	global_store_dword v3, v2, s[10:11] offset:2048 sc0 sc1
	s_mov_b64 exec, s[6:7]

.LBB0_250:
	v_readlane_b32 s4, v254, 49
	s_add_i32 s14, s4, 3
	v_readlane_b32 s4, v252, 9
	v_readlane_b32 s5, v252, 10
	s_cmp_ge_i32 s14, s5
	s_cbranch_scc1 .LBB0_304
	s_waitcnt vmcnt(0)
	s_waitcnt lgkmcnt(0)
	s_barrier
	s_mov_b64 s[4:5], exec
	v_readlane_b32 s6, v252, 31
	v_readlane_b32 s7, v252, 32
	s_mul_i32 s72, s62, 5
	s_add_i32 s72, s72, 3
	s_and_b64 s[6:7], s[4:5], s[6:7]
	s_mov_b64 exec, s[6:7]
	s_cbranch_execz .LBB0_303
	v_readlane_b32 s10, v253, 57
	v_readlane_b32 s11, v253, 58
	v_readlane_b32 s73, v254, 38
	v_mov_b32_e32 v2, 1
	s_nop 4
	global_atomic_add v3, v1, v2, s[10:11] sc0
	v_mov_b32_e32 v0, s73
	v_readlane_b32 s73, v254, 39
	ds_read_b32 v4, v0
	s_nop 1
	v_mov_b32_e32 v0, s73
	ds_read_b32 v5, v0
	s_waitcnt lgkmcnt(0)
	v_mul_lo_u32 v4, v4, s72
	v_mul_lo_u32 v5, v5, s72
	s_waitcnt vmcnt(0)
	v_add_u32_e32 v3, 1, v3
	v_cmp_eq_u32_e32 vcc, v3, v4
	s_cbranch_vccz .Lxb2_poll
	buffer_wbl2 sc1
	v_readlane_b32 s10, v253, 61
	v_readlane_b32 s11, v253, 62
	s_waitcnt vmcnt(0)
	s_nop 4
	global_atomic_add v3, v1, v2, s[10:11] sc0
	s_waitcnt vmcnt(0)
	v_add_u32_e32 v3, 1, v3
	v_cmp_eq_u32_e32 vcc, v3, v5
	s_cbranch_vccz .Lxb2_poll
	s_add_u32 s10, s30, 0x8400
	s_addc_u32 s11, s31, 0
	s_mov_b64 exec, -1
	v_mbcnt_lo_u32_b32 v3, -1, 0
	v_mbcnt_hi_u32_b32 v3, -1, v3
	s_sub_u32 s73, s72, 1
	v_mov_b32_e32 v2, s73
	v_lshlrev_b32_e32 v3, 5, v3
	s_nop 1
	global_store_dword v3, v2, s[10:11] sc0 sc1
	global_store_dword v3, v2, s[10:11] offset:2048 sc0 sc1
	s_add_u32 s10, s10, 0x1000
	s_addc_u32 s11, s11, 0
	global_store_dword v3, v2, s[10:11] sc0 sc1
	global_store_dword v3, v2, s[10:11] offset:2048 sc0 sc1
	s_mov_b64 exec, s[6:7]

.LBB0_409:
	v_readlane_b32 s4, v254, 49
	s_add_i32 s14, s4, 4
	v_readlane_b32 s4, v252, 9
	v_readlane_b32 s5, v252, 10
	s_cmp_ge_i32 s14, s5
	s_cbranch_scc1 .LBB0_421
	s_waitcnt vmcnt(0)
	s_barrier
	s_mov_b32 s53, 0x2aaaaaab
	s_mov_b32 s62, s70
	s_mov_b64 s[4:5], exec
	v_readlane_b32 s6, v252, 31
	v_readlane_b32 s7, v252, 32
	s_mul_i32 s72, s62, 5
	s_add_i32 s72, s72, 4
	s_and_b64 s[6:7], s[4:5], s[6:7]
	s_mov_b64 exec, s[6:7]
	s_cbranch_execz .LBB0_463
	v_readlane_b32 s10, v253, 57
	v_readlane_b32 s11, v253, 58
	v_readlane_b32 s73, v254, 38
	v_mov_b32_e32 v2, 1
	s_nop 4
	global_atomic_add v3, v1, v2, s[10:11] sc0
	v_mov_b32_e32 v0, s73
	v_readlane_b32 s73, v254, 39
	ds_read_b32 v4, v0
	s_nop 1
	v_mov_b32_e32 v0, s73
	ds_read_b32 v5, v0
	s_waitcnt lgkmcnt(0)
	v_mul_lo_u32 v4, v4, s72
	v_mul_lo_u32 v5, v5, s72
	s_waitcnt vmcnt(0)
	v_add_u32_e32 v3, 1, v3
	v_cmp_eq_u32_e32 vcc, v3, v4
	s_cbranch_vccz .Lxb3_poll
	buffer_wbl2 sc1
	v_readlane_b32 s10, v253, 61
	v_readlane_b32 s11, v253, 62
	s_waitcnt vmcnt(0)
	s_nop 4
	global_atomic_add v3, v1, v2, s[10:11] sc0
	s_waitcnt vmcnt(0)
	v_add_u32_e32 v3, 1, v3
	v_cmp_eq_u32_e32 vcc, v3, v5
	s_cbranch_vccz .Lxb3_poll
	s_add_u32 s10, s30, 0x8400
	s_addc_u32 s11, s31, 0
	s_mov_b64 exec, -1
	v_mbcnt_lo_u32_b32 v3, -1, 0
	v_mbcnt_hi_u32_b32 v3, -1, v3
	s_sub_u32 s73, s72, 1
	v_mov_b32_e32 v2, s73
	v_lshlrev_b32_e32 v3, 5, v3
	s_nop 1
	global_store_dword v3, v2, s[10:11] sc0 sc1
	global_store_dword v3, v2, s[10:11] offset:2048 sc0 sc1
	s_add_u32 s10, s10, 0x1000
	s_addc_u32 s11, s11, 0
	global_store_dword v3, v2, s[10:11] sc0 sc1
	global_store_dword v3, v2, s[10:11] offset:2048 sc0 sc1
	s_mov_b64 exec, s[6:7]

.LBB0_510:
	s_or_b64 exec, exec, s[10:11]
	v_readlane_b32 s4, v254, 49
	s_add_i32 s8, s4, 5
	v_readlane_b32 s4, v252, 9
	v_readlane_b32 s5, v252, 10
	s_cmp_ge_i32 s8, s5
	s_cbranch_scc1 .LBB0_564
	s_waitcnt vmcnt(0)
	s_waitcnt lgkmcnt(0)
	s_barrier
	s_mov_b64 s[4:5], exec
	v_readlane_b32 s6, v252, 31
	v_readlane_b32 s7, v252, 32
	s_mul_i32 s72, s62, 5
	s_add_i32 s72, s72, 5
	s_and_b64 s[6:7], s[4:5], s[6:7]
	s_mov_b64 exec, s[6:7]
	s_cbranch_execz .LBB0_563
	v_readlane_b32 s10, v253, 57
	v_readlane_b32 s11, v253, 58
	v_readlane_b32 s73, v254, 38
	v_mov_b32_e32 v2, 1
	s_nop 4
	global_atomic_add v3, v1, v2, s[10:11] sc0
	v_mov_b32_e32 v0, s73
	v_readlane_b32 s73, v254, 39
	ds_read_b32 v4, v0
	s_nop 1
	v_mov_b32_e32 v0, s73
	ds_read_b32 v5, v0
	s_waitcnt lgkmcnt(0)
	v_mul_lo_u32 v4, v4, s72
	v_mul_lo_u32 v5, v5, s72
	s_waitcnt vmcnt(0)
	v_add_u32_e32 v3, 1, v3
	v_cmp_eq_u32_e32 vcc, v3, v4
	s_cbranch_vccz .Lxb4_poll
	buffer_wbl2 sc1
	v_readlane_b32 s10, v253, 61
	v_readlane_b32 s11, v253, 62
	s_waitcnt vmcnt(0)
	s_nop 4
	global_atomic_add v3, v1, v2, s[10:11] sc0
	s_waitcnt vmcnt(0)
	v_add_u32_e32 v3, 1, v3
	v_cmp_eq_u32_e32 vcc, v3, v5
	s_cbranch_vccz .Lxb4_poll
	s_add_u32 s10, s30, 0x8400
	s_addc_u32 s11, s31, 0
	s_mov_b64 exec, -1
	v_mbcnt_lo_u32_b32 v3, -1, 0
	v_mbcnt_hi_u32_b32 v3, -1, v3
	s_sub_u32 s73, s72, 1
	v_mov_b32_e32 v2, s73
	v_lshlrev_b32_e32 v3, 5, v3
	s_nop 1
	global_store_dword v3, v2, s[10:11] sc0 sc1
	global_store_dword v3, v2, s[10:11] offset:2048 sc0 sc1
	s_add_u32 s10, s10, 0x1000
	s_addc_u32 s11, s11, 0
	global_store_dword v3, v2, s[10:11] sc0 sc1
	global_store_dword v3, v2, s[10:11] offset:2048 sc0 sc1
	s_mov_b64 exec, s[6:7]

.Lxb5_lean:
	s_mov_b64 s[4:5], exec
	v_readlane_b32 s6, v252, 31
	v_readlane_b32 s7, v252, 32
	s_mul_i32 s72, s62, 5
	s_add_i32 s72, s72, 6
	s_and_b64 s[6:7], s[4:5], s[6:7]
	s_mov_b64 exec, s[6:7]
	s_cbranch_execz .LBB0_113
	v_readlane_b32 s10, v253, 57
	v_readlane_b32 s11, v253, 58
	v_readlane_b32 s73, v254, 38
	v_mov_b32_e32 v2, 1
	s_nop 4
	global_atomic_add v3, v1, v2, s[10:11] sc0
	v_mov_b32_e32 v0, s73
	v_readlane_b32 s73, v254, 39
	ds_read_b32 v4, v0
	s_nop 1
	v_mov_b32_e32 v0, s73
	ds_read_b32 v5, v0
	s_waitcnt lgkmcnt(0)
	v_mul_lo_u32 v4, v4, s72
	v_mul_lo_u32 v5, v5, s72
	s_waitcnt vmcnt(0)
	v_add_u32_e32 v3, 1, v3
	v_cmp_eq_u32_e32 vcc, v3, v4
	s_cbranch_vccz .Lxb5_poll
	buffer_wbl2 sc1
	v_readlane_b32 s10, v253, 61
	v_readlane_b32 s11, v253, 62
	s_waitcnt vmcnt(0)
	s_nop 4
	global_atomic_add v3, v1, v2, s[10:11] sc0
	s_waitcnt vmcnt(0)
	v_add_u32_e32 v3, 1, v3
	v_cmp_eq_u32_e32 vcc, v3, v5
	s_cbranch_vccz .Lxb5_poll
	s_add_u32 s10, s30, 0x8400
	s_addc_u32 s11, s31, 0
	s_mov_b64 exec, -1
	v_mbcnt_lo_u32_b32 v3, -1, 0
	v_mbcnt_hi_u32_b32 v3, -1, v3
	s_sub_u32 s73, s72, 1
	v_mov_b32_e32 v2, s73
	v_lshlrev_b32_e32 v3, 5, v3
	s_nop 1
	global_store_dword v3, v2, s[10:11] sc0 sc1
	global_store_dword v3, v2, s[10:11] offset:2048 sc0 sc1
	s_add_u32 s10, s10, 0x1000
	s_addc_u32 s11, s11, 0
	global_store_dword v3, v2, s[10:11] sc0 sc1
	global_store_dword v3, v2, s[10:11] offset:2048 sc0 sc1
	s_mov_b64 exec, s[6:7]
